# SwiGLU GEMM: row-scale partial sums and bias vectors prefetched in the peeled first K-iteration; epilogue has no global load wait and no table-build barrier
# speedup vs baseline: 1.0101x; 1.0101x over previous
.LBB0_251:
	s_ashr_i32 s13, s12, 31
	s_lshl_b64 s[14:15], s[12:13], 19
	s_add_u32 s14, s29, s14
	s_addc_u32 s15, s38, s15
	s_and_b64 s[16:17], s[4:5], exec
	s_cselect_b32 s13, s15, s23
	s_cselect_b32 s19, s14, s22
	s_ashr_i32 s11, s10, 31
	s_lshl_b64 s[16:17], s[10:11], 19
	s_add_u32 s16, s39, s16
	s_addc_u32 s17, s40, s17
	s_and_b64 s[24:25], s[4:5], exec
	s_cselect_b32 s11, s17, s21
	s_cselect_b32 s61, s16, s20
	s_add_u32 s62, s20, 0x100
	s_addc_u32 s63, s21, 0
	s_add_u32 s20, s22, 0x40080
	s_addc_u32 s21, s23, 0
	s_mov_b32 s68, -2
	s_add_u32 s22, s20, 0xfffc0080
	s_addc_u32 s23, s21, -1
	s_add_i32 s64, 0, 0x10000
	s_cmp_eq_u32 s68, 12
	s_cselect_b32 s25, s13, s23
	s_cselect_b32 s24, s19, s22
	s_cselect_b32 s23, s11, s63
	s_cselect_b32 s22, s61, s62
	s_lshl_b32 s74, s18, 8
	v_add_u32_e32 v178, s74, v168
	v_ashrrev_i32_e32 v179, 31, v178
	v_lshlrev_b64 v[178:179], 6, v[178:179]
	v_lshl_add_u64 v[178:179], s[70:71], 0, v[178:179]
	s_and_saveexec_b64 s[78:79], s[2:3]
	global_load_dwordx4 v[238:241], v[178:179], off
	global_load_dwordx4 v[242:245], v[178:179], off offset:16
	global_load_dwordx4 v[246:249], v[178:179], off offset:32
	global_load_dwordx4 v[250:253], v[178:179], off offset:48
	s_mov_b64 exec, s[78:79]
	s_add_i32 s69, 0, 0x14000
	v_add_u32_e32 v140, s64, v167
	v_add_u32_e32 v164, s69, v167
	ds_read_b128 v[48:51], v140
	ds_read_b128 v[56:59], v140 offset:1024
	ds_read_b128 v[136:139], v140 offset:2048
	ds_read_b128 v[140:143], v140 offset:3072
	ds_read_b128 v[156:159], v164
	ds_read_b128 v[160:163], v164 offset:1024
	ds_read_b128 v[182:185], v164 offset:2048
	ds_read_b128 v[186:189], v164 offset:3072
	v_lshl_add_u64 v[164:165], s[20:21], 0, v[154:155]
	s_add_i32 m0, s49, 0xc000
	ds_read_b128 v[190:193], v172
	ds_read_b128 v[194:197], v172 offset:1024
	ds_read_b128 v[198:201], v172 offset:2048
	ds_read_b128 v[202:205], v172 offset:3072
	ds_read_b128 v[206:209], v172 offset:4096
	ds_read_b128 v[210:213], v172 offset:5120
	ds_read_b128 v[228:231], v172 offset:6144
	ds_read_b128 v[232:235], v172 offset:7168
	global_load_lds_dwordx4 v[164:165], off
	v_lshl_add_u64 v[164:165], s[20:21], 0, v[152:153]
	s_add_i32 m0, s49, 0xe000
	s_nop 0
	global_load_lds_dwordx4 v[164:165], off
	s_waitcnt vmcnt(12)
	s_waitcnt lgkmcnt(0)
	s_barrier
	s_setprio 1
	v_mfma_f32_16x16x32_bf16 v[132:135], v[48:51], v[190:193], 0
	v_mfma_f32_16x16x32_bf16 v[124:127], v[136:139], v[190:193], 0
	v_mfma_f32_16x16x32_bf16 v[116:119], v[48:51], v[198:201], 0
	v_mfma_f32_16x16x32_bf16 v[112:115], v[136:139], v[198:201], 0
	v_mfma_f32_16x16x32_bf16 v[100:103], v[48:51], v[206:209], 0
	v_mfma_f32_16x16x32_bf16 v[96:99], v[136:139], v[206:209], 0
	v_mfma_f32_16x16x32_bf16 v[84:87], v[48:51], v[228:231], 0
	v_mfma_f32_16x16x32_bf16 v[80:83], v[136:139], v[228:231], 0
	v_mfma_f32_16x16x32_bf16 v[132:135], v[56:59], v[194:197], v[132:135]
	v_mfma_f32_16x16x32_bf16 v[124:127], v[140:143], v[194:197], v[124:127]
	v_mfma_f32_16x16x32_bf16 v[116:119], v[56:59], v[202:205], v[116:119]
	v_mfma_f32_16x16x32_bf16 v[112:115], v[140:143], v[202:205], v[112:115]
	v_mfma_f32_16x16x32_bf16 v[100:103], v[56:59], v[210:213], v[100:103]
	v_mfma_f32_16x16x32_bf16 v[96:99], v[140:143], v[210:213], v[96:99]
	v_mfma_f32_16x16x32_bf16 v[84:87], v[56:59], v[232:235], v[84:87]
	v_mfma_f32_16x16x32_bf16 v[80:83], v[140:143], v[232:235], v[80:83]
	v_mfma_f32_16x16x32_bf16 v[128:131], v[156:159], v[190:193], 0
	v_mfma_f32_16x16x32_bf16 v[120:123], v[182:185], v[190:193], 0
	v_mfma_f32_16x16x32_bf16 v[108:111], v[156:159], v[198:201], 0
	v_mfma_f32_16x16x32_bf16 v[104:107], v[182:185], v[198:201], 0
	v_mfma_f32_16x16x32_bf16 v[92:95], v[156:159], v[206:209], 0
	v_mfma_f32_16x16x32_bf16 v[88:91], v[182:185], v[206:209], 0
	v_mfma_f32_16x16x32_bf16 v[76:79], v[156:159], v[228:231], 0
	v_mfma_f32_16x16x32_bf16 v[72:75], v[182:185], v[228:231], 0
	v_mfma_f32_16x16x32_bf16 v[128:131], v[160:163], v[194:197], v[128:131]
	v_mfma_f32_16x16x32_bf16 v[120:123], v[186:189], v[194:197], v[120:123]
	v_mfma_f32_16x16x32_bf16 v[108:111], v[160:163], v[202:205], v[108:111]
	v_mfma_f32_16x16x32_bf16 v[104:107], v[186:189], v[202:205], v[104:107]
	s_setprio 2
	s_barrier
	v_mfma_f32_16x16x32_bf16 v[92:95], v[160:163], v[210:213], v[92:95]
	v_mfma_f32_16x16x32_bf16 v[88:91], v[186:189], v[210:213], v[88:91]
	v_mfma_f32_16x16x32_bf16 v[76:79], v[160:163], v[232:235], v[76:79]
	v_mfma_f32_16x16x32_bf16 v[72:75], v[186:189], v[232:235], v[72:75]
	s_setprio 0
	s_add_i32 s64, s64, s41
	v_lshl_add_u64 v[164:165], s[22:23], 0, v[148:149]
	s_mov_b32 m0, s64
	ds_read_b128 v[190:193], v172 offset:16384
	ds_read_b128 v[194:197], v172 offset:17408
	ds_read_b128 v[198:201], v172 offset:18432
	ds_read_b128 v[202:205], v172 offset:19456
	ds_read_b128 v[206:209], v172 offset:20480
	ds_read_b128 v[210:213], v172 offset:21504
	ds_read_b128 v[228:231], v172 offset:22528
	ds_read_b128 v[232:235], v172 offset:23552
	global_load_lds_dwordx4 v[164:165], off
	s_add_i32 m0, s64, 0x2000
	s_add_u32 s64, s22, 0x40000
	v_lshl_add_u64 v[220:221], s[22:23], 0, v[144:145]
	s_addc_u32 s65, s23, 0
	s_add_i32 s69, s69, s41
	global_load_lds_dwordx4 v[220:221], off
	v_lshl_add_u64 v[222:223], s[64:65], 0, v[148:149]
	s_mov_b32 m0, s69
	v_lshl_add_u64 v[226:227], s[24:25], 0, v[146:147]
	global_load_lds_dwordx4 v[222:223], off
	v_lshl_add_u64 v[222:223], s[64:65], 0, v[144:145]
	s_add_i32 m0, s69, 0x2000
	s_nop 0
	global_load_lds_dwordx4 v[222:223], off
	v_lshl_add_u64 v[222:223], s[24:25], 0, v[150:151]
	s_mov_b32 m0, s49
	s_nop 0
	global_load_lds_dwordx4 v[222:223], off
	s_mov_b32 m0, s50
	s_nop 0
	global_load_lds_dwordx4 v[226:227], off
	s_waitcnt vmcnt(8)
	s_waitcnt lgkmcnt(0)
	s_barrier
	s_setprio 1
	v_mfma_f32_16x16x32_bf16 v[68:71], v[48:51], v[190:193], 0
	v_mfma_f32_16x16x32_bf16 v[64:67], v[136:139], v[190:193], 0
	v_mfma_f32_16x16x32_bf16 v[44:47], v[48:51], v[198:201], 0
	v_mfma_f32_16x16x32_bf16 v[40:43], v[136:139], v[198:201], 0
	v_mfma_f32_16x16x32_bf16 v[28:31], v[48:51], v[206:209], 0
	v_mfma_f32_16x16x32_bf16 v[24:27], v[136:139], v[206:209], 0
	v_mfma_f32_16x16x32_bf16 v[12:15], v[48:51], v[228:231], 0
	v_mfma_f32_16x16x32_bf16 v[8:11], v[136:139], v[228:231], 0
	v_mfma_f32_16x16x32_bf16 v[68:71], v[56:59], v[194:197], v[68:71]
	v_mfma_f32_16x16x32_bf16 v[64:67], v[140:143], v[194:197], v[64:67]
	v_mfma_f32_16x16x32_bf16 v[44:47], v[56:59], v[202:205], v[44:47]
	v_mfma_f32_16x16x32_bf16 v[40:43], v[140:143], v[202:205], v[40:43]
	v_mfma_f32_16x16x32_bf16 v[28:31], v[56:59], v[210:213], v[28:31]
	v_mfma_f32_16x16x32_bf16 v[24:27], v[140:143], v[210:213], v[24:27]
	v_mfma_f32_16x16x32_bf16 v[12:15], v[56:59], v[232:235], v[12:15]
	v_mfma_f32_16x16x32_bf16 v[8:11], v[140:143], v[232:235], v[8:11]
	v_mfma_f32_16x16x32_bf16 v[52:55], v[182:185], v[190:193], 0
	v_mfma_f32_16x16x32_bf16 v[36:39], v[156:159], v[198:201], 0
	v_mfma_f32_16x16x32_bf16 v[32:35], v[182:185], v[198:201], 0
	v_mfma_f32_16x16x32_bf16 v[20:23], v[156:159], v[206:209], 0
	v_mfma_f32_16x16x32_bf16 v[16:19], v[182:185], v[206:209], 0
	v_mfma_f32_16x16x32_bf16 v[4:7], v[156:159], v[228:231], 0
	v_mfma_f32_16x16x32_bf16 v[0:3], v[182:185], v[228:231], 0
	v_mfma_f32_16x16x32_bf16 v[48:51], v[156:159], v[190:193], 0
	v_mfma_f32_16x16x32_bf16 v[52:55], v[186:189], v[194:197], v[52:55]
	v_mfma_f32_16x16x32_bf16 v[36:39], v[160:163], v[202:205], v[36:39]
	v_mfma_f32_16x16x32_bf16 v[32:35], v[186:189], v[202:205], v[32:35]
	v_mfma_f32_16x16x32_bf16 v[20:23], v[160:163], v[210:213], v[20:23]
	s_setprio 2
	s_barrier
	v_mfma_f32_16x16x32_bf16 v[16:19], v[186:189], v[210:213], v[16:19]
	v_mfma_f32_16x16x32_bf16 v[4:7], v[160:163], v[232:235], v[4:7]
	v_mfma_f32_16x16x32_bf16 v[0:3], v[186:189], v[232:235], v[0:3]
	v_mfma_f32_16x16x32_bf16 v[48:51], v[160:163], v[194:197], v[48:51]
	s_setprio 0
	s_and_saveexec_b64 s[78:79], s[2:3]
	v_add_f32_e32 v238, v238, v239
	v_add_f32_e32 v240, v240, v241
	v_add_f32_e32 v242, v242, v243
	v_add_f32_e32 v244, v244, v245
	v_add_f32_e32 v246, v246, v247
	v_add_f32_e32 v248, v248, v249
	v_add_f32_e32 v250, v250, v251
	v_add_f32_e32 v252, v252, v253
	v_add_f32_e32 v238, v238, v240
	v_add_f32_e32 v242, v242, v244
	v_add_f32_e32 v246, v246, v248
	v_add_f32_e32 v250, v250, v252
	v_add_f32_e32 v238, v238, v242
	v_add_f32_e32 v246, v246, v250
	v_add_f32_e32 v238, v238, v246
	v_fmamk_f32 v238, v238, 0x3a800000, v216
	v_rsq_f32_e32 v238, v238
	s_nop 0
	ds_write_b32 v169, v238
	s_mov_b64 exec, s[78:79]
	s_add_i32 s64, 0, 0x18000
	s_add_i32 s65, 0, 0x1c000
	v_add_u32_e32 v140, s64, v167
	v_add_u32_e32 v173, s65, v167
	ds_read_b128 v[56:59], v140
	ds_read_b128 v[60:63], v140 offset:1024
	ds_read_b128 v[136:139], v140 offset:2048
	ds_read_b128 v[140:143], v140 offset:3072
	ds_read_b128 v[156:159], v173
	ds_read_b128 v[160:163], v173 offset:1024
	ds_read_b128 v[182:185], v173 offset:2048
	ds_read_b128 v[186:189], v173 offset:3072
	s_add_u32 s24, s24, 0x40000
	s_addc_u32 s25, s25, 0
	s_mov_b32 m0, s51
	v_lshl_add_u64 v[236:237], s[24:25], 0, v[150:151]
	ds_read_b128 v[190:193], v172 offset:32768
	ds_read_b128 v[194:197], v172 offset:33792
	ds_read_b128 v[198:201], v172 offset:34816
	ds_read_b128 v[202:205], v172 offset:35840
	ds_read_b128 v[206:209], v172 offset:36864
	ds_read_b128 v[210:213], v172 offset:37888
	ds_read_b128 v[228:231], v172 offset:38912
	ds_read_b128 v[232:235], v172 offset:39936
	global_load_lds_dwordx4 v[236:237], off
	v_lshl_add_u64 v[236:237], s[24:25], 0, v[146:147]
	s_mov_b32 m0, s52
	s_nop 0
	global_load_lds_dwordx4 v[236:237], off
	s_waitcnt vmcnt(8)
	s_waitcnt lgkmcnt(0)
	s_barrier
	s_setprio 1
	v_mfma_f32_16x16x32_bf16 v[132:135], v[56:59], v[190:193], v[132:135]
	v_mfma_f32_16x16x32_bf16 v[124:127], v[136:139], v[190:193], v[124:127]
	v_mfma_f32_16x16x32_bf16 v[116:119], v[56:59], v[198:201], v[116:119]
	v_mfma_f32_16x16x32_bf16 v[112:115], v[136:139], v[198:201], v[112:115]
	v_mfma_f32_16x16x32_bf16 v[100:103], v[56:59], v[206:209], v[100:103]
	v_mfma_f32_16x16x32_bf16 v[96:99], v[136:139], v[206:209], v[96:99]
	v_mfma_f32_16x16x32_bf16 v[84:87], v[56:59], v[228:231], v[84:87]
	v_mfma_f32_16x16x32_bf16 v[80:83], v[136:139], v[228:231], v[80:83]
	v_mfma_f32_16x16x32_bf16 v[132:135], v[60:63], v[194:197], v[132:135]
	v_mfma_f32_16x16x32_bf16 v[124:127], v[140:143], v[194:197], v[124:127]
	v_mfma_f32_16x16x32_bf16 v[116:119], v[60:63], v[202:205], v[116:119]
	v_mfma_f32_16x16x32_bf16 v[112:115], v[140:143], v[202:205], v[112:115]
	v_mfma_f32_16x16x32_bf16 v[100:103], v[60:63], v[210:213], v[100:103]
	v_mfma_f32_16x16x32_bf16 v[96:99], v[140:143], v[210:213], v[96:99]
	v_mfma_f32_16x16x32_bf16 v[84:87], v[60:63], v[232:235], v[84:87]
	v_mfma_f32_16x16x32_bf16 v[80:83], v[140:143], v[232:235], v[80:83]
	v_mfma_f32_16x16x32_bf16 v[128:131], v[156:159], v[190:193], v[128:131]
	v_mfma_f32_16x16x32_bf16 v[120:123], v[182:185], v[190:193], v[120:123]
	v_mfma_f32_16x16x32_bf16 v[108:111], v[156:159], v[198:201], v[108:111]
	v_mfma_f32_16x16x32_bf16 v[104:107], v[182:185], v[198:201], v[104:107]
	v_mfma_f32_16x16x32_bf16 v[92:95], v[156:159], v[206:209], v[92:95]
	v_mfma_f32_16x16x32_bf16 v[88:91], v[182:185], v[206:209], v[88:91]
	v_mfma_f32_16x16x32_bf16 v[76:79], v[156:159], v[228:231], v[76:79]
	v_mfma_f32_16x16x32_bf16 v[72:75], v[182:185], v[228:231], v[72:75]
	v_mfma_f32_16x16x32_bf16 v[128:131], v[160:163], v[194:197], v[128:131]
	v_mfma_f32_16x16x32_bf16 v[120:123], v[186:189], v[194:197], v[120:123]
	v_mfma_f32_16x16x32_bf16 v[108:111], v[160:163], v[202:205], v[108:111]
	v_mfma_f32_16x16x32_bf16 v[104:107], v[186:189], v[202:205], v[104:107]
	s_setprio 2
	s_barrier
	v_mfma_f32_16x16x32_bf16 v[92:95], v[160:163], v[210:213], v[92:95]
	v_mfma_f32_16x16x32_bf16 v[88:91], v[186:189], v[210:213], v[88:91]
	v_mfma_f32_16x16x32_bf16 v[76:79], v[160:163], v[232:235], v[76:79]
	v_mfma_f32_16x16x32_bf16 v[72:75], v[186:189], v[232:235], v[72:75]
	s_setprio 0
	s_min_i32 s74, s18, 0x80
	s_ashr_i32 s74, s74, 3
	s_mul_hi_i32 s75, s74, 0x5800
	s_mulk_i32 s74, 0x5800
	s_add_u32 s74, s53, s74
	s_addc_u32 s75, s54, s75
	s_lshl_b32 s76, s60, 8
	s_ashr_i32 s77, s76, 31
	s_lshl_b64 s[76:77], s[76:77], 2
	s_add_u32 s74, s74, s76
	s_addc_u32 s75, s75, s77
	s_add_u32 s74, s74, s59
	s_addc_u32 s75, s75, 0
	v_lshl_add_u64 v[178:179], s[74:75], 0, v[176:177]
	global_load_dwordx4 v[238:241], v[178:179], off
	global_load_dwordx4 v[242:245], v[178:179], off offset:16
	global_load_dwordx4 v[246:249], v[178:179], off offset:512
	global_load_dwordx4 v[250:253], v[178:179], off offset:528
	s_add_i32 s24, s64, s41
	v_lshl_add_u64 v[164:165], v[164:165], 0, s[34:35]
	s_mov_b32 m0, s24
	ds_read_b128 v[190:193], v172 offset:49152
	ds_read_b128 v[194:197], v172 offset:50176
	ds_read_b128 v[198:201], v172 offset:51200
	ds_read_b128 v[202:205], v172 offset:52224
	ds_read_b128 v[206:209], v172 offset:53248
	ds_read_b128 v[210:213], v172 offset:54272
	ds_read_b128 v[228:231], v172 offset:55296
	ds_read_b128 v[232:235], v172 offset:56320
	global_load_lds_dwordx4 v[164:165], off
	s_add_i32 m0, s24, 0x2000
	s_add_u32 s22, s22, 0x40080
	v_lshl_add_u64 v[164:165], v[220:221], 0, s[34:35]
	s_addc_u32 s23, s23, 0
	s_add_i32 s24, s65, s41
	global_load_lds_dwordx4 v[164:165], off
	v_lshl_add_u64 v[164:165], s[22:23], 0, v[148:149]
	s_mov_b32 m0, s24
	s_nop 0
	global_load_lds_dwordx4 v[164:165], off
	v_lshl_add_u64 v[164:165], s[22:23], 0, v[144:145]
	s_add_i32 m0, s24, 0x2000
	s_nop 0
	global_load_lds_dwordx4 v[164:165], off
	v_lshl_add_u64 v[164:165], v[222:223], 0, s[34:35]
	s_mov_b32 m0, s55
	s_nop 0
	global_load_lds_dwordx4 v[164:165], off
	v_lshl_add_u64 v[164:165], v[226:227], 0, s[34:35]
	s_mov_b32 m0, s56
	s_nop 0
	global_load_lds_dwordx4 v[164:165], off
	s_waitcnt vmcnt(12)
	s_waitcnt lgkmcnt(0)
	s_barrier
	s_setprio 1
	v_mfma_f32_16x16x32_bf16 v[68:71], v[56:59], v[190:193], v[68:71]
	v_mfma_f32_16x16x32_bf16 v[64:67], v[136:139], v[190:193], v[64:67]
	v_mfma_f32_16x16x32_bf16 v[44:47], v[56:59], v[198:201], v[44:47]
	v_mfma_f32_16x16x32_bf16 v[40:43], v[136:139], v[198:201], v[40:43]
	v_mfma_f32_16x16x32_bf16 v[28:31], v[56:59], v[206:209], v[28:31]
	v_mfma_f32_16x16x32_bf16 v[24:27], v[136:139], v[206:209], v[24:27]
	v_mfma_f32_16x16x32_bf16 v[12:15], v[56:59], v[228:231], v[12:15]
	v_mfma_f32_16x16x32_bf16 v[8:11], v[136:139], v[228:231], v[8:11]
	v_mfma_f32_16x16x32_bf16 v[68:71], v[60:63], v[194:197], v[68:71]
	v_mfma_f32_16x16x32_bf16 v[64:67], v[140:143], v[194:197], v[64:67]
	v_mfma_f32_16x16x32_bf16 v[44:47], v[60:63], v[202:205], v[44:47]
	v_mfma_f32_16x16x32_bf16 v[40:43], v[140:143], v[202:205], v[40:43]
	v_mfma_f32_16x16x32_bf16 v[28:31], v[60:63], v[210:213], v[28:31]
	v_mfma_f32_16x16x32_bf16 v[24:27], v[140:143], v[210:213], v[24:27]
	v_mfma_f32_16x16x32_bf16 v[12:15], v[60:63], v[232:235], v[12:15]
	v_mfma_f32_16x16x32_bf16 v[8:11], v[140:143], v[232:235], v[8:11]
	v_mfma_f32_16x16x32_bf16 v[48:51], v[156:159], v[190:193], v[48:51]
	v_mfma_f32_16x16x32_bf16 v[60:63], v[160:163], v[194:197], v[48:51]
	v_mfma_f32_16x16x32_bf16 v[48:51], v[182:185], v[190:193], v[52:55]
	v_mfma_f32_16x16x32_bf16 v[36:39], v[156:159], v[198:201], v[36:39]
	v_mfma_f32_16x16x32_bf16 v[32:35], v[182:185], v[198:201], v[32:35]
	v_mfma_f32_16x16x32_bf16 v[20:23], v[156:159], v[206:209], v[20:23]
	v_mfma_f32_16x16x32_bf16 v[16:19], v[182:185], v[206:209], v[16:19]
	v_mfma_f32_16x16x32_bf16 v[4:7], v[156:159], v[228:231], v[4:7]
	v_mfma_f32_16x16x32_bf16 v[0:3], v[182:185], v[228:231], v[0:3]
	v_mfma_f32_16x16x32_bf16 v[52:55], v[186:189], v[194:197], v[48:51]
	v_mfma_f32_16x16x32_bf16 v[36:39], v[160:163], v[202:205], v[36:39]
	v_mfma_f32_16x16x32_bf16 v[32:35], v[186:189], v[202:205], v[32:35]
	s_setprio 2
	s_barrier
	v_mfma_f32_16x16x32_bf16 v[20:23], v[160:163], v[210:213], v[20:23]
	v_mfma_f32_16x16x32_bf16 v[16:19], v[186:189], v[210:213], v[16:19]
	v_mfma_f32_16x16x32_bf16 v[4:7], v[160:163], v[232:235], v[4:7]
	v_mfma_f32_16x16x32_bf16 v[0:3], v[186:189], v[232:235], v[0:3]
	s_setprio 0
	s_add_i32 s68, s68, 2
	s_add_u32 s62, s62, 0x100
	s_addc_u32 s63, s63, 0
	s_add_u32 s20, s20, 0x100
	s_addc_u32 s21, s21, 0
	s_cmp_gt_u32 s68, 13

.LBB0_255:
	s_lshl_b32 s11, s18, 8
	s_mov_b64 s[18:19], -1
	ds_read_b32 v182, v170
	ds_read_b32 v183, v170 offset:64
	ds_read_b32 v184, v170 offset:128
	ds_read_b32 v185, v170 offset:192
	ds_read_b32 v186, v170 offset:512
	ds_read_b32 v187, v170 offset:576
	ds_read_b32 v188, v170 offset:640
	ds_read_b32 v189, v170 offset:704
	v_add_u32_e32 v203, s11, v166
	v_lshl_or_b32 v202, s60, 7, v171
	v_lshlrev_b32_e32 v202, 1, v202
	v_mad_u32_u24 v202, v203, s86, v202
	s_waitcnt lgkmcnt(0)
	v_fma_f32 v132, v132, v182, v238
	v_fma_f32 v133, v133, v182, v239
	v_fma_f32 v134, v134, v182, v240
	v_fma_f32 v135, v135, v182, v241
	v_fma_f32 v124, v124, v182, v242
	v_fma_f32 v125, v125, v182, v243
	v_fma_f32 v126, v126, v182, v244
	v_fma_f32 v127, v127, v182, v245
	v_fma_f32 v128, v128, v182, v246
	v_fma_f32 v129, v129, v182, v247
	v_fma_f32 v130, v130, v182, v248
	v_fma_f32 v131, v131, v182, v249
	v_fma_f32 v120, v120, v182, v250
	v_fma_f32 v121, v121, v182, v251
	v_fma_f32 v122, v122, v182, v252
	v_fma_f32 v123, v123, v182, v253
	v_mul_f32_e32 v190, 0xbfb8aa3b, v132
	v_mul_f32_e32 v191, 0xbfb8aa3b, v133
	v_mul_f32_e32 v192, 0xbfb8aa3b, v134
	v_mul_f32_e32 v193, 0xbfb8aa3b, v135
	v_mul_f32_e32 v194, 0xbfb8aa3b, v124
	v_mul_f32_e32 v195, 0xbfb8aa3b, v125
	v_mul_f32_e32 v196, 0xbfb8aa3b, v126
	v_mul_f32_e32 v197, 0xbfb8aa3b, v127
	v_exp_f32_e32 v190, v190
	v_exp_f32_e32 v191, v191
	v_exp_f32_e32 v192, v192
	v_exp_f32_e32 v193, v193
	v_exp_f32_e32 v194, v194
	v_exp_f32_e32 v195, v195
	v_exp_f32_e32 v196, v196
	v_exp_f32_e32 v197, v197
	v_add_f32_e32 v190, 1.0, v190
	v_add_f32_e32 v191, 1.0, v191
	v_add_f32_e32 v192, 1.0, v192
	v_add_f32_e32 v193, 1.0, v193
	v_add_f32_e32 v194, 1.0, v194
	v_add_f32_e32 v195, 1.0, v195
	v_add_f32_e32 v196, 1.0, v196
	v_add_f32_e32 v197, 1.0, v197
	v_rcp_f32_e32 v190, v190
	v_rcp_f32_e32 v191, v191
	v_rcp_f32_e32 v192, v192
	v_rcp_f32_e32 v193, v193
	v_rcp_f32_e32 v194, v194
	v_rcp_f32_e32 v195, v195
	v_rcp_f32_e32 v196, v196
	v_rcp_f32_e32 v197, v197
	v_mul_f32_e32 v132, v132, v190
	v_mul_f32_e32 v133, v133, v191
	v_mul_f32_e32 v134, v134, v192
	v_mul_f32_e32 v135, v135, v193
	v_mul_f32_e32 v124, v124, v194
	v_mul_f32_e32 v125, v125, v195
	v_mul_f32_e32 v126, v126, v196
	v_mul_f32_e32 v127, v127, v197
	v_mul_f32_e32 v132, v132, v128
	v_mul_f32_e32 v133, v133, v129
	v_mul_f32_e32 v134, v134, v130
	v_mul_f32_e32 v135, v135, v131
	v_mul_f32_e32 v124, v124, v120
	v_mul_f32_e32 v125, v125, v121
	v_mul_f32_e32 v126, v126, v122
	v_mul_f32_e32 v127, v127, v123
	v_cvt_pk_bf16_f32 v198, v132, v133
	v_cvt_pk_bf16_f32 v199, v134, v135
	v_cvt_pk_bf16_f32 v200, v124, v125
	v_cvt_pk_bf16_f32 v201, v126, v127
	global_store_dwordx4 v202, v[198:201], s[6:7]
	v_fma_f32 v116, v116, v183, v238
	v_fma_f32 v117, v117, v183, v239
	v_fma_f32 v118, v118, v183, v240
	v_fma_f32 v119, v119, v183, v241
	v_fma_f32 v112, v112, v183, v242
	v_fma_f32 v113, v113, v183, v243
	v_fma_f32 v114, v114, v183, v244
	v_fma_f32 v115, v115, v183, v245
	v_fma_f32 v108, v108, v183, v246
	v_fma_f32 v109, v109, v183, v247
	v_fma_f32 v110, v110, v183, v248
	v_fma_f32 v111, v111, v183, v249
	v_fma_f32 v104, v104, v183, v250
	v_fma_f32 v105, v105, v183, v251
	v_fma_f32 v106, v106, v183, v252
	v_fma_f32 v107, v107, v183, v253
	v_mul_f32_e32 v190, 0xbfb8aa3b, v116
	v_mul_f32_e32 v191, 0xbfb8aa3b, v117
	v_mul_f32_e32 v192, 0xbfb8aa3b, v118
	v_mul_f32_e32 v193, 0xbfb8aa3b, v119
	v_mul_f32_e32 v194, 0xbfb8aa3b, v112
	v_mul_f32_e32 v195, 0xbfb8aa3b, v113
	v_mul_f32_e32 v196, 0xbfb8aa3b, v114
	v_mul_f32_e32 v197, 0xbfb8aa3b, v115
	v_exp_f32_e32 v190, v190
	v_exp_f32_e32 v191, v191
	v_exp_f32_e32 v192, v192
	v_exp_f32_e32 v193, v193
	v_exp_f32_e32 v194, v194
	v_exp_f32_e32 v195, v195
	v_exp_f32_e32 v196, v196
	v_exp_f32_e32 v197, v197
	v_add_f32_e32 v190, 1.0, v190
	v_add_f32_e32 v191, 1.0, v191
	v_add_f32_e32 v192, 1.0, v192
	v_add_f32_e32 v193, 1.0, v193
	v_add_f32_e32 v194, 1.0, v194
	v_add_f32_e32 v195, 1.0, v195
	v_add_f32_e32 v196, 1.0, v196
	v_add_f32_e32 v197, 1.0, v197
	v_rcp_f32_e32 v190, v190
	v_rcp_f32_e32 v191, v191
	v_rcp_f32_e32 v192, v192
	v_rcp_f32_e32 v193, v193
	v_rcp_f32_e32 v194, v194
	v_rcp_f32_e32 v195, v195
	v_rcp_f32_e32 v196, v196
	v_rcp_f32_e32 v197, v197
	v_mul_f32_e32 v116, v116, v190
	v_mul_f32_e32 v117, v117, v191
	v_mul_f32_e32 v118, v118, v192
	v_mul_f32_e32 v119, v119, v193
	v_mul_f32_e32 v112, v112, v194
	v_mul_f32_e32 v113, v113, v195
	v_mul_f32_e32 v114, v114, v196
	v_mul_f32_e32 v115, v115, v197
	v_mul_f32_e32 v116, v116, v108
	v_mul_f32_e32 v117, v117, v109
	v_mul_f32_e32 v118, v118, v110
	v_mul_f32_e32 v119, v119, v111
	v_mul_f32_e32 v112, v112, v104
	v_mul_f32_e32 v113, v113, v105
	v_mul_f32_e32 v114, v114, v106
	v_mul_f32_e32 v115, v115, v107
	v_cvt_pk_bf16_f32 v198, v116, v117
	v_cvt_pk_bf16_f32 v199, v118, v119
	v_cvt_pk_bf16_f32 v200, v112, v113
	v_cvt_pk_bf16_f32 v201, v114, v115
	v_add_u32_e32 v203, 0x16000, v202
	s_nop 0
	global_store_dwordx4 v203, v[198:201], s[6:7]
	v_fma_f32 v100, v100, v184, v238
	v_fma_f32 v101, v101, v184, v239
	v_fma_f32 v102, v102, v184, v240
	v_fma_f32 v103, v103, v184, v241
	v_fma_f32 v96, v96, v184, v242
	v_fma_f32 v97, v97, v184, v243
	v_fma_f32 v98, v98, v184, v244
	v_fma_f32 v99, v99, v184, v245
	v_fma_f32 v92, v92, v184, v246
	v_fma_f32 v93, v93, v184, v247
	v_fma_f32 v94, v94, v184, v248
	v_fma_f32 v95, v95, v184, v249
	v_fma_f32 v88, v88, v184, v250
	v_fma_f32 v89, v89, v184, v251
	v_fma_f32 v90, v90, v184, v252
	v_fma_f32 v91, v91, v184, v253
	v_mul_f32_e32 v190, 0xbfb8aa3b, v100
	v_mul_f32_e32 v191, 0xbfb8aa3b, v101
	v_mul_f32_e32 v192, 0xbfb8aa3b, v102
	v_mul_f32_e32 v193, 0xbfb8aa3b, v103
	v_mul_f32_e32 v194, 0xbfb8aa3b, v96
	v_mul_f32_e32 v195, 0xbfb8aa3b, v97
	v_mul_f32_e32 v196, 0xbfb8aa3b, v98
	v_mul_f32_e32 v197, 0xbfb8aa3b, v99
	v_exp_f32_e32 v190, v190
	v_exp_f32_e32 v191, v191
	v_exp_f32_e32 v192, v192
	v_exp_f32_e32 v193, v193
	v_exp_f32_e32 v194, v194
	v_exp_f32_e32 v195, v195
	v_exp_f32_e32 v196, v196
	v_exp_f32_e32 v197, v197
	v_add_f32_e32 v190, 1.0, v190
	v_add_f32_e32 v191, 1.0, v191
	v_add_f32_e32 v192, 1.0, v192
	v_add_f32_e32 v193, 1.0, v193
	v_add_f32_e32 v194, 1.0, v194
	v_add_f32_e32 v195, 1.0, v195
	v_add_f32_e32 v196, 1.0, v196
	v_add_f32_e32 v197, 1.0, v197
	v_rcp_f32_e32 v190, v190
	v_rcp_f32_e32 v191, v191
	v_rcp_f32_e32 v192, v192
	v_rcp_f32_e32 v193, v193
	v_rcp_f32_e32 v194, v194
	v_rcp_f32_e32 v195, v195
	v_rcp_f32_e32 v196, v196
	v_rcp_f32_e32 v197, v197
	v_mul_f32_e32 v100, v100, v190
	v_mul_f32_e32 v101, v101, v191
	v_mul_f32_e32 v102, v102, v192
	v_mul_f32_e32 v103, v103, v193
	v_mul_f32_e32 v96, v96, v194
	v_mul_f32_e32 v97, v97, v195
	v_mul_f32_e32 v98, v98, v196
	v_mul_f32_e32 v99, v99, v197
	v_mul_f32_e32 v100, v100, v92
	v_mul_f32_e32 v101, v101, v93
	v_mul_f32_e32 v102, v102, v94
	v_mul_f32_e32 v103, v103, v95
	v_mul_f32_e32 v96, v96, v88
	v_mul_f32_e32 v97, v97, v89
	v_mul_f32_e32 v98, v98, v90
	v_mul_f32_e32 v99, v99, v91
	v_cvt_pk_bf16_f32 v198, v100, v101
	v_cvt_pk_bf16_f32 v199, v102, v103
	v_cvt_pk_bf16_f32 v200, v96, v97
	v_cvt_pk_bf16_f32 v201, v98, v99
	v_add_u32_e32 v203, 0x2c000, v202
	s_nop 0
	global_store_dwordx4 v203, v[198:201], s[6:7]
	v_fma_f32 v84, v84, v185, v238
	v_fma_f32 v85, v85, v185, v239
	v_fma_f32 v86, v86, v185, v240
	v_fma_f32 v87, v87, v185, v241
	v_fma_f32 v80, v80, v185, v242
	v_fma_f32 v81, v81, v185, v243
	v_fma_f32 v82, v82, v185, v244
	v_fma_f32 v83, v83, v185, v245
	v_fma_f32 v76, v76, v185, v246
	v_fma_f32 v77, v77, v185, v247
	v_fma_f32 v78, v78, v185, v248
	v_fma_f32 v79, v79, v185, v249
	v_fma_f32 v72, v72, v185, v250
	v_fma_f32 v73, v73, v185, v251
	v_fma_f32 v74, v74, v185, v252
	v_fma_f32 v75, v75, v185, v253
	v_mul_f32_e32 v190, 0xbfb8aa3b, v84
	v_mul_f32_e32 v191, 0xbfb8aa3b, v85
	v_mul_f32_e32 v192, 0xbfb8aa3b, v86
	v_mul_f32_e32 v193, 0xbfb8aa3b, v87
	v_mul_f32_e32 v194, 0xbfb8aa3b, v80
	v_mul_f32_e32 v195, 0xbfb8aa3b, v81
	v_mul_f32_e32 v196, 0xbfb8aa3b, v82
	v_mul_f32_e32 v197, 0xbfb8aa3b, v83
	v_exp_f32_e32 v190, v190
	v_exp_f32_e32 v191, v191
	v_exp_f32_e32 v192, v192
	v_exp_f32_e32 v193, v193
	v_exp_f32_e32 v194, v194
	v_exp_f32_e32 v195, v195
	v_exp_f32_e32 v196, v196
	v_exp_f32_e32 v197, v197
	v_add_f32_e32 v190, 1.0, v190
	v_add_f32_e32 v191, 1.0, v191
	v_add_f32_e32 v192, 1.0, v192
	v_add_f32_e32 v193, 1.0, v193
	v_add_f32_e32 v194, 1.0, v194
	v_add_f32_e32 v195, 1.0, v195
	v_add_f32_e32 v196, 1.0, v196
	v_add_f32_e32 v197, 1.0, v197
	v_rcp_f32_e32 v190, v190
	v_rcp_f32_e32 v191, v191
	v_rcp_f32_e32 v192, v192
	v_rcp_f32_e32 v193, v193
	v_rcp_f32_e32 v194, v194
	v_rcp_f32_e32 v195, v195
	v_rcp_f32_e32 v196, v196
	v_rcp_f32_e32 v197, v197
	v_mul_f32_e32 v84, v84, v190
	v_mul_f32_e32 v85, v85, v191
	v_mul_f32_e32 v86, v86, v192
	v_mul_f32_e32 v87, v87, v193
	v_mul_f32_e32 v80, v80, v194
	v_mul_f32_e32 v81, v81, v195
	v_mul_f32_e32 v82, v82, v196
	v_mul_f32_e32 v83, v83, v197
	v_mul_f32_e32 v84, v84, v76
	v_mul_f32_e32 v85, v85, v77
	v_mul_f32_e32 v86, v86, v78
	v_mul_f32_e32 v87, v87, v79
	v_mul_f32_e32 v80, v80, v72
	v_mul_f32_e32 v81, v81, v73
	v_mul_f32_e32 v82, v82, v74
	v_mul_f32_e32 v83, v83, v75
	v_cvt_pk_bf16_f32 v198, v84, v85
	v_cvt_pk_bf16_f32 v199, v86, v87
	v_cvt_pk_bf16_f32 v200, v80, v81
	v_cvt_pk_bf16_f32 v201, v82, v83
	v_add_u32_e32 v203, 0x42000, v202
	s_nop 0
	global_store_dwordx4 v203, v[198:201], s[6:7]
	v_fma_f32 v68, v68, v186, v238
	v_fma_f32 v69, v69, v186, v239
	v_fma_f32 v70, v70, v186, v240
	v_fma_f32 v71, v71, v186, v241
	v_fma_f32 v64, v64, v186, v242
	v_fma_f32 v65, v65, v186, v243
	v_fma_f32 v66, v66, v186, v244
	v_fma_f32 v67, v67, v186, v245
	v_fma_f32 v60, v60, v186, v246
	v_fma_f32 v61, v61, v186, v247
	v_fma_f32 v62, v62, v186, v248
	v_fma_f32 v63, v63, v186, v249
	v_fma_f32 v52, v52, v186, v250
	v_fma_f32 v53, v53, v186, v251
	v_fma_f32 v54, v54, v186, v252
	v_fma_f32 v55, v55, v186, v253
	v_mul_f32_e32 v190, 0xbfb8aa3b, v68
	v_mul_f32_e32 v191, 0xbfb8aa3b, v69
	v_mul_f32_e32 v192, 0xbfb8aa3b, v70
	v_mul_f32_e32 v193, 0xbfb8aa3b, v71
	v_mul_f32_e32 v194, 0xbfb8aa3b, v64
	v_mul_f32_e32 v195, 0xbfb8aa3b, v65
	v_mul_f32_e32 v196, 0xbfb8aa3b, v66
	v_mul_f32_e32 v197, 0xbfb8aa3b, v67
	v_exp_f32_e32 v190, v190
	v_exp_f32_e32 v191, v191
	v_exp_f32_e32 v192, v192
	v_exp_f32_e32 v193, v193
	v_exp_f32_e32 v194, v194
	v_exp_f32_e32 v195, v195
	v_exp_f32_e32 v196, v196
	v_exp_f32_e32 v197, v197
	v_add_f32_e32 v190, 1.0, v190
	v_add_f32_e32 v191, 1.0, v191
	v_add_f32_e32 v192, 1.0, v192
	v_add_f32_e32 v193, 1.0, v193
	v_add_f32_e32 v194, 1.0, v194
	v_add_f32_e32 v195, 1.0, v195
	v_add_f32_e32 v196, 1.0, v196
	v_add_f32_e32 v197, 1.0, v197
	v_rcp_f32_e32 v190, v190
	v_rcp_f32_e32 v191, v191
	v_rcp_f32_e32 v192, v192
	v_rcp_f32_e32 v193, v193
	v_rcp_f32_e32 v194, v194
	v_rcp_f32_e32 v195, v195
	v_rcp_f32_e32 v196, v196
	v_rcp_f32_e32 v197, v197
	v_mul_f32_e32 v68, v68, v190
	v_mul_f32_e32 v69, v69, v191
	v_mul_f32_e32 v70, v70, v192
	v_mul_f32_e32 v71, v71, v193
	v_mul_f32_e32 v64, v64, v194
	v_mul_f32_e32 v65, v65, v195
	v_mul_f32_e32 v66, v66, v196
	v_mul_f32_e32 v67, v67, v197
	v_mul_f32_e32 v68, v68, v60
	v_mul_f32_e32 v69, v69, v61
	v_mul_f32_e32 v70, v70, v62
	v_mul_f32_e32 v71, v71, v63
	v_mul_f32_e32 v64, v64, v52
	v_mul_f32_e32 v65, v65, v53
	v_mul_f32_e32 v66, v66, v54
	v_mul_f32_e32 v67, v67, v55
	v_cvt_pk_bf16_f32 v198, v68, v69
	v_cvt_pk_bf16_f32 v199, v70, v71
	v_cvt_pk_bf16_f32 v200, v64, v65
	v_cvt_pk_bf16_f32 v201, v66, v67
	v_add_u32_e32 v203, 0xb0000, v202
	s_nop 0
	global_store_dwordx4 v203, v[198:201], s[6:7]
	v_fma_f32 v44, v44, v187, v238
	v_fma_f32 v45, v45, v187, v239
	v_fma_f32 v46, v46, v187, v240
	v_fma_f32 v47, v47, v187, v241
	v_fma_f32 v40, v40, v187, v242
	v_fma_f32 v41, v41, v187, v243
	v_fma_f32 v42, v42, v187, v244
	v_fma_f32 v43, v43, v187, v245
	v_fma_f32 v36, v36, v187, v246
	v_fma_f32 v37, v37, v187, v247
	v_fma_f32 v38, v38, v187, v248
	v_fma_f32 v39, v39, v187, v249
	v_fma_f32 v32, v32, v187, v250
	v_fma_f32 v33, v33, v187, v251
	v_fma_f32 v34, v34, v187, v252
	v_fma_f32 v35, v35, v187, v253
	v_mul_f32_e32 v190, 0xbfb8aa3b, v44
	v_mul_f32_e32 v191, 0xbfb8aa3b, v45
	v_mul_f32_e32 v192, 0xbfb8aa3b, v46
	v_mul_f32_e32 v193, 0xbfb8aa3b, v47
	v_mul_f32_e32 v194, 0xbfb8aa3b, v40
	v_mul_f32_e32 v195, 0xbfb8aa3b, v41
	v_mul_f32_e32 v196, 0xbfb8aa3b, v42
	v_mul_f32_e32 v197, 0xbfb8aa3b, v43
	v_exp_f32_e32 v190, v190
	v_exp_f32_e32 v191, v191
	v_exp_f32_e32 v192, v192
	v_exp_f32_e32 v193, v193
	v_exp_f32_e32 v194, v194
	v_exp_f32_e32 v195, v195
	v_exp_f32_e32 v196, v196
	v_exp_f32_e32 v197, v197
	v_add_f32_e32 v190, 1.0, v190
	v_add_f32_e32 v191, 1.0, v191
	v_add_f32_e32 v192, 1.0, v192
	v_add_f32_e32 v193, 1.0, v193
	v_add_f32_e32 v194, 1.0, v194
	v_add_f32_e32 v195, 1.0, v195
	v_add_f32_e32 v196, 1.0, v196
	v_add_f32_e32 v197, 1.0, v197
	v_rcp_f32_e32 v190, v190
	v_rcp_f32_e32 v191, v191
	v_rcp_f32_e32 v192, v192
	v_rcp_f32_e32 v193, v193
	v_rcp_f32_e32 v194, v194
	v_rcp_f32_e32 v195, v195
	v_rcp_f32_e32 v196, v196
	v_rcp_f32_e32 v197, v197
	v_mul_f32_e32 v44, v44, v190
	v_mul_f32_e32 v45, v45, v191
	v_mul_f32_e32 v46, v46, v192
	v_mul_f32_e32 v47, v47, v193
	v_mul_f32_e32 v40, v40, v194
	v_mul_f32_e32 v41, v41, v195
	v_mul_f32_e32 v42, v42, v196
	v_mul_f32_e32 v43, v43, v197
	v_mul_f32_e32 v44, v44, v36
	v_mul_f32_e32 v45, v45, v37
	v_mul_f32_e32 v46, v46, v38
	v_mul_f32_e32 v47, v47, v39
	v_mul_f32_e32 v40, v40, v32
	v_mul_f32_e32 v41, v41, v33
	v_mul_f32_e32 v42, v42, v34
	v_mul_f32_e32 v43, v43, v35
	v_cvt_pk_bf16_f32 v198, v44, v45
	v_cvt_pk_bf16_f32 v199, v46, v47
	v_cvt_pk_bf16_f32 v200, v40, v41
	v_cvt_pk_bf16_f32 v201, v42, v43
	v_add_u32_e32 v203, 0xc6000, v202
	s_nop 0
	global_store_dwordx4 v203, v[198:201], s[6:7]
	v_fma_f32 v28, v28, v188, v238
	v_fma_f32 v29, v29, v188, v239
	v_fma_f32 v30, v30, v188, v240
	v_fma_f32 v31, v31, v188, v241
	v_fma_f32 v24, v24, v188, v242
	v_fma_f32 v25, v25, v188, v243
	v_fma_f32 v26, v26, v188, v244
	v_fma_f32 v27, v27, v188, v245
	v_fma_f32 v20, v20, v188, v246
	v_fma_f32 v21, v21, v188, v247
	v_fma_f32 v22, v22, v188, v248
	v_fma_f32 v23, v23, v188, v249
	v_fma_f32 v16, v16, v188, v250
	v_fma_f32 v17, v17, v188, v251
	v_fma_f32 v18, v18, v188, v252
	v_fma_f32 v19, v19, v188, v253
	v_mul_f32_e32 v190, 0xbfb8aa3b, v28
	v_mul_f32_e32 v191, 0xbfb8aa3b, v29
	v_mul_f32_e32 v192, 0xbfb8aa3b, v30
	v_mul_f32_e32 v193, 0xbfb8aa3b, v31
	v_mul_f32_e32 v194, 0xbfb8aa3b, v24
	v_mul_f32_e32 v195, 0xbfb8aa3b, v25
	v_mul_f32_e32 v196, 0xbfb8aa3b, v26
	v_mul_f32_e32 v197, 0xbfb8aa3b, v27
	v_exp_f32_e32 v190, v190
	v_exp_f32_e32 v191, v191
	v_exp_f32_e32 v192, v192
	v_exp_f32_e32 v193, v193
	v_exp_f32_e32 v194, v194
	v_exp_f32_e32 v195, v195
	v_exp_f32_e32 v196, v196
	v_exp_f32_e32 v197, v197
	v_add_f32_e32 v190, 1.0, v190
	v_add_f32_e32 v191, 1.0, v191
	v_add_f32_e32 v192, 1.0, v192
	v_add_f32_e32 v193, 1.0, v193
	v_add_f32_e32 v194, 1.0, v194
	v_add_f32_e32 v195, 1.0, v195
	v_add_f32_e32 v196, 1.0, v196
	v_add_f32_e32 v197, 1.0, v197
	v_rcp_f32_e32 v190, v190
	v_rcp_f32_e32 v191, v191
	v_rcp_f32_e32 v192, v192
	v_rcp_f32_e32 v193, v193
	v_rcp_f32_e32 v194, v194
	v_rcp_f32_e32 v195, v195
	v_rcp_f32_e32 v196, v196
	v_rcp_f32_e32 v197, v197
	v_mul_f32_e32 v28, v28, v190
	v_mul_f32_e32 v29, v29, v191
	v_mul_f32_e32 v30, v30, v192
	v_mul_f32_e32 v31, v31, v193
	v_mul_f32_e32 v24, v24, v194
	v_mul_f32_e32 v25, v25, v195
	v_mul_f32_e32 v26, v26, v196
	v_mul_f32_e32 v27, v27, v197
	v_mul_f32_e32 v28, v28, v20
	v_mul_f32_e32 v29, v29, v21
	v_mul_f32_e32 v30, v30, v22
	v_mul_f32_e32 v31, v31, v23
	v_mul_f32_e32 v24, v24, v16
	v_mul_f32_e32 v25, v25, v17
	v_mul_f32_e32 v26, v26, v18
	v_mul_f32_e32 v27, v27, v19
	v_cvt_pk_bf16_f32 v198, v28, v29
	v_cvt_pk_bf16_f32 v199, v30, v31
	v_cvt_pk_bf16_f32 v200, v24, v25
	v_cvt_pk_bf16_f32 v201, v26, v27
	v_add_u32_e32 v203, 0xdc000, v202
	s_nop 0
	global_store_dwordx4 v203, v[198:201], s[6:7]
	v_fma_f32 v12, v12, v189, v238
	v_fma_f32 v13, v13, v189, v239
	v_fma_f32 v14, v14, v189, v240
	v_fma_f32 v15, v15, v189, v241
	v_fma_f32 v8, v8, v189, v242
	v_fma_f32 v9, v9, v189, v243
	v_fma_f32 v10, v10, v189, v244
	v_fma_f32 v11, v11, v189, v245
	v_fma_f32 v4, v4, v189, v246
	v_fma_f32 v5, v5, v189, v247
	v_fma_f32 v6, v6, v189, v248
	v_fma_f32 v7, v7, v189, v249
	v_fma_f32 v0, v0, v189, v250
	v_fma_f32 v1, v1, v189, v251
	v_fma_f32 v2, v2, v189, v252
	v_fma_f32 v3, v3, v189, v253
	v_mul_f32_e32 v190, 0xbfb8aa3b, v12
	v_mul_f32_e32 v191, 0xbfb8aa3b, v13
	v_mul_f32_e32 v192, 0xbfb8aa3b, v14
	v_mul_f32_e32 v193, 0xbfb8aa3b, v15
	v_mul_f32_e32 v194, 0xbfb8aa3b, v8
	v_mul_f32_e32 v195, 0xbfb8aa3b, v9
	v_mul_f32_e32 v196, 0xbfb8aa3b, v10
	v_mul_f32_e32 v197, 0xbfb8aa3b, v11
	v_exp_f32_e32 v190, v190
	v_exp_f32_e32 v191, v191
	v_exp_f32_e32 v192, v192
	v_exp_f32_e32 v193, v193
	v_exp_f32_e32 v194, v194
	v_exp_f32_e32 v195, v195
	v_exp_f32_e32 v196, v196
	v_exp_f32_e32 v197, v197
	v_add_f32_e32 v190, 1.0, v190
	v_add_f32_e32 v191, 1.0, v191
	v_add_f32_e32 v192, 1.0, v192
	v_add_f32_e32 v193, 1.0, v193
	v_add_f32_e32 v194, 1.0, v194
	v_add_f32_e32 v195, 1.0, v195
	v_add_f32_e32 v196, 1.0, v196
	v_add_f32_e32 v197, 1.0, v197
	v_rcp_f32_e32 v190, v190
	v_rcp_f32_e32 v191, v191
	v_rcp_f32_e32 v192, v192
	v_rcp_f32_e32 v193, v193
	v_rcp_f32_e32 v194, v194
	v_rcp_f32_e32 v195, v195
	v_rcp_f32_e32 v196, v196
	v_rcp_f32_e32 v197, v197
	v_mul_f32_e32 v12, v12, v190
	v_mul_f32_e32 v13, v13, v191
	v_mul_f32_e32 v14, v14, v192
	v_mul_f32_e32 v15, v15, v193
	v_mul_f32_e32 v8, v8, v194
	v_mul_f32_e32 v9, v9, v195
	v_mul_f32_e32 v10, v10, v196
	v_mul_f32_e32 v11, v11, v197
	v_mul_f32_e32 v12, v12, v4
	v_mul_f32_e32 v13, v13, v5
	v_mul_f32_e32 v14, v14, v6
	v_mul_f32_e32 v15, v15, v7
	v_mul_f32_e32 v8, v8, v0
	v_mul_f32_e32 v9, v9, v1
	v_mul_f32_e32 v10, v10, v2
	v_mul_f32_e32 v11, v11, v3
	v_cvt_pk_bf16_f32 v198, v12, v13
	v_cvt_pk_bf16_f32 v199, v14, v15
	v_cvt_pk_bf16_f32 v200, v8, v9
	v_cvt_pk_bf16_f32 v201, v10, v11
	v_add_u32_e32 v203, 0xf2000, v202
	s_nop 0
	global_store_dwordx4 v203, v[198:201], s[6:7]
	s_andn2_b64 vcc, exec, s[4:5]
	s_cbranch_vccnz .LBB0_248
	s_andn2_b64 vcc, exec, s[0:1]
	s_cbranch_vccnz .LBB0_247
	s_barrier
	s_branch .LBB0_247
